# RG-LRU scan loops (chunk aggregate, carry, rescan): loads of 16 steps issued together behind counted vmcnt instead of one round trip per step
# speedup vs baseline: 1.0331x; 1.0331x over previous
; __device__ __forceinline__ unsigned cvt_pk_bf16(float lo, float hi) { unsigned r; asm("v_cvt_pk_bf16_f32 %0, %1, %2" : "=v"(r) : "v"(lo), "v"(hi)); return r; }
; __device__ __forceinline__ float bfhi(unsigned w) { return __uint_as_float(w & 0xffff0000u); }
; __device__ __forceinline__ float bf2f(bf16_t v) { return __uint_as_float(((unsigned)v) << 16); }
; __global__ void __launch_bounds__(512, 2) fwd_megakernel(Params PK) {
;     ...
;             { const unsigned* LRW = (const unsigned*)(ws + WS_LRA); const float* AGP = (const float*)(ws + WS_AGG); const float* AGH = AGP + 128 * 1024;
;                 bf16_t* Ob = (bf16_t*)(ws + WS_O) + (size_t)1 * MT * DBR;
;                 for (size_t id = gtid; id < (size_t)128 * 1024; id += gstride) { const int ch = (int)(id & 1023), bc = (int)(id >> 10), b = bc >> 5, ck = bc & 31; const size_t base = (size_t)bc * 128 * DBR + ch;
;                     float h = 0.f; const float sc = fmaxf(1.0f - __expf(-((const float*)(ws + WS_PEW1))[512 + ch]), 1e-30f) * (1.0f / 65535.0f);
;                     for (int j = 0; j < ck; ++j) { const size_t a = (size_t)(b * 32 + j) * 1024 + ch; h = AGP[a] * h + AGH[a]; }
; #pragma unroll 8
;                     for (int t = 0; t < 128; ++t) { const unsigned w = LRW[base + (size_t)t * DBR]; const float a = 1.0f - (float)(w & 0xffffu) * sc, g = bfhi(w); h = a * h + g;
;                         const float sg = bf2f(Hh[((size_t)bc * 128 + t) * LDH + C_GB + ch]);
;                         Ob[base + (size_t)t * DBR] = (bf16_t)(cvt_pk_bf16(h * sg, 0.f) & 0xffffu); } } }
.LBB0_759:
	v_readfirstlane_b32 s14, v7
	v_add_u32_e32 v13, 0x80000, v0
	s_mov_b64 vcc, s[6:7]
.Llru_carry_batch:
	global_load_dword v24, v0, vcc
	global_load_dword v25, v13, vcc
	s_add_u32 vcc_lo, vcc_lo, 0x1000
	s_addc_u32 vcc_hi, vcc_hi, 0
	global_load_dword v26, v0, vcc
	global_load_dword v27, v13, vcc
	s_add_u32 vcc_lo, vcc_lo, 0x1000
	s_addc_u32 vcc_hi, vcc_hi, 0
	global_load_dword v28, v0, vcc
	global_load_dword v29, v13, vcc
	s_add_u32 vcc_lo, vcc_lo, 0x1000
	s_addc_u32 vcc_hi, vcc_hi, 0
	global_load_dword v30, v0, vcc
	global_load_dword v31, v13, vcc
	s_add_u32 vcc_lo, vcc_lo, 0x1000
	s_addc_u32 vcc_hi, vcc_hi, 0
	global_load_dword v32, v0, vcc
	global_load_dword v33, v13, vcc
	s_add_u32 vcc_lo, vcc_lo, 0x1000
	s_addc_u32 vcc_hi, vcc_hi, 0
	global_load_dword v34, v0, vcc
	global_load_dword v35, v13, vcc
	s_add_u32 vcc_lo, vcc_lo, 0x1000
	s_addc_u32 vcc_hi, vcc_hi, 0
	global_load_dword v36, v0, vcc
	global_load_dword v37, v13, vcc
	s_add_u32 vcc_lo, vcc_lo, 0x1000
	s_addc_u32 vcc_hi, vcc_hi, 0
	global_load_dword v38, v0, vcc
	global_load_dword v39, v13, vcc
	s_add_u32 vcc_lo, vcc_lo, 0x1000
	s_addc_u32 vcc_hi, vcc_hi, 0
	s_waitcnt vmcnt(14)
	v_fma_f32 v14, v14, v24, v25
	s_cmp_le_u32 s14, 0x1000
	s_cbranch_scc1 .Llru_carry_done
	s_waitcnt vmcnt(12)
	v_fma_f32 v14, v14, v26, v27
	s_cmp_le_u32 s14, 0x2000
	s_cbranch_scc1 .Llru_carry_done
	s_waitcnt vmcnt(10)
	v_fma_f32 v14, v14, v28, v29
	s_cmp_le_u32 s14, 0x3000
	s_cbranch_scc1 .Llru_carry_done
	s_waitcnt vmcnt(8)
	v_fma_f32 v14, v14, v30, v31
	s_cmp_le_u32 s14, 0x4000
	s_cbranch_scc1 .Llru_carry_done
	s_waitcnt vmcnt(6)
	v_fma_f32 v14, v14, v32, v33
	s_cmp_le_u32 s14, 0x5000
	s_cbranch_scc1 .Llru_carry_done
	s_waitcnt vmcnt(4)
	v_fma_f32 v14, v14, v34, v35
	s_cmp_le_u32 s14, 0x6000
	s_cbranch_scc1 .Llru_carry_done
	s_waitcnt vmcnt(2)
	v_fma_f32 v14, v14, v36, v37
	s_cmp_le_u32 s14, 0x7000
	s_cbranch_scc1 .Llru_carry_done
	s_waitcnt vmcnt(0)
	v_fma_f32 v14, v14, v38, v39
	s_sub_u32 s14, s14, 0x8000
	s_cmp_lg_u32 s14, 0
	s_cbranch_scc1 .Llru_carry_batch
.Llru_carry_done:
.LBB0_761:
	s_or_b64 exec, exec, s[12:13]
	s_waitcnt vmcnt(0)
	v_mul_f32_e32 v11, 0xbfb8aa3b, v11
	v_exp_f32_e32 v11, v11
	s_mov_b32 s14, 0x2b0000
	v_mad_u64_u32 v[4:5], s[12:13], v8, s14, 0
	v_lshlrev_b32_e32 v0, 1, v6
	v_lshlrev_b64 v[6:7], 18, v[8:9]
	v_or_b32_e32 v4, v4, v0
	v_or_b32_e32 v6, v6, v0
	v_sub_f32_e32 v0, 1.0, v11
	v_mad_u32_u24 v5, v9, s14, v5
	v_lshlrev_b64 v[8:9], 19, v[8:9]
	v_max_f32_e32 v0, 0xda24260, v0
	v_or_b32_e32 v8, v8, v10
	v_mul_f32_e32 v0, 0x37800080, v0
	s_movk_i32 s12, 0x80
.LBB0_762:
	v_add_u32_e32 v56, 0x20e04000, v8
	v_add_u32_e32 v40, 0xb205000, v4
	global_load_dword v24, v56, s[68:69] offset:-4096
	global_load_ushort v40, v40, s[68:69]
	v_add_u32_e32 v41, 0xb20a600, v4
	global_load_dword v25, v56, s[68:69]
	global_load_ushort v41, v41, s[68:69]
	v_add_u32_e32 v57, 0x20e06000, v8
	v_add_u32_e32 v42, 0xb20fc00, v4
	global_load_dword v26, v57, s[68:69] offset:-4096
	global_load_ushort v42, v42, s[68:69]
	v_add_u32_e32 v43, 0xb215200, v4
	global_load_dword v27, v57, s[68:69]
	global_load_ushort v43, v43, s[68:69]
	v_add_u32_e32 v58, 0x20e08000, v8
	v_add_u32_e32 v44, 0xb21a800, v4
	global_load_dword v28, v58, s[68:69] offset:-4096
	global_load_ushort v44, v44, s[68:69]
	v_add_u32_e32 v45, 0xb21fe00, v4
	global_load_dword v29, v58, s[68:69]
	global_load_ushort v45, v45, s[68:69]
	v_add_u32_e32 v59, 0x20e0a000, v8
	v_add_u32_e32 v46, 0xb225400, v4
	global_load_dword v30, v59, s[68:69] offset:-4096
	global_load_ushort v46, v46, s[68:69]
	v_add_u32_e32 v47, 0xb22aa00, v4
	global_load_dword v31, v59, s[68:69]
	global_load_ushort v47, v47, s[68:69]
	v_add_u32_e32 v60, 0x20e0c000, v8
	v_add_u32_e32 v48, 0xb230000, v4
	global_load_dword v32, v60, s[68:69] offset:-4096
	global_load_ushort v48, v48, s[68:69]
	v_add_u32_e32 v49, 0xb235600, v4
	global_load_dword v33, v60, s[68:69]
	global_load_ushort v49, v49, s[68:69]
	v_add_u32_e32 v61, 0x20e0e000, v8
	v_add_u32_e32 v50, 0xb23ac00, v4
	global_load_dword v34, v61, s[68:69] offset:-4096
	global_load_ushort v50, v50, s[68:69]
	v_add_u32_e32 v51, 0xb240200, v4
	global_load_dword v35, v61, s[68:69]
	global_load_ushort v51, v51, s[68:69]
	v_add_u32_e32 v62, 0x20e10000, v8
	v_add_u32_e32 v52, 0xb245800, v4
	global_load_dword v36, v62, s[68:69] offset:-4096
	global_load_ushort v52, v52, s[68:69]
	v_add_u32_e32 v53, 0xb24ae00, v4
	global_load_dword v37, v62, s[68:69]
	global_load_ushort v53, v53, s[68:69]
	v_add_u32_e32 v63, 0x20e12000, v8
	v_add_u32_e32 v54, 0xb250400, v4
	global_load_dword v38, v63, s[68:69] offset:-4096
	global_load_ushort v54, v54, s[68:69]
	v_add_u32_e32 v55, 0xb255a00, v4
	global_load_dword v39, v63, s[68:69]
	global_load_ushort v55, v55, s[68:69]
	v_add_u32_e32 v8, 0x10000, v8
	v_add_u32_e32 v4, 0x56000, v4
	s_add_i32 s12, s12, -16
	v_add_u32_e32 v22, 0x2ae04000, v6
	s_waitcnt vmcnt(30)
	v_cvt_f32_u32_sdwa v21, v24 dst_sel:DWORD dst_unused:UNUSED_PAD src0_sel:WORD_0
	v_and_b32_e32 v17, 0xffff0000, v24
	v_fma_f32 v21, -v0, v21, 1.0
	v_fmac_f32_e32 v17, v14, v21
	v_lshlrev_b32_e32 v40, 16, v40
	v_mul_f32_e32 v40, v17, v40
	v_cvt_pk_bf16_f32 v40, v40, v1
	global_store_short v22, v40, s[68:69] offset:-4096
	s_waitcnt vmcnt(29)
	v_cvt_f32_u32_sdwa v21, v25 dst_sel:DWORD dst_unused:UNUSED_PAD src0_sel:WORD_0
	v_and_b32_e32 v14, 0xffff0000, v25
	v_fma_f32 v21, -v0, v21, 1.0
	v_fmac_f32_e32 v14, v17, v21
	v_lshlrev_b32_e32 v41, 16, v41
	v_mul_f32_e32 v41, v14, v41
	v_cvt_pk_bf16_f32 v41, v41, v1
	global_store_short v22, v41, s[68:69] offset:-2048
	s_waitcnt vmcnt(28)
; __device__ __forceinline__ unsigned cvt_pk_bf16(float lo, float hi) { unsigned r; asm("v_cvt_pk_bf16_f32 %0, %1, %2" : "=v"(r) : "v"(lo), "v"(hi)); return r; }
; __device__ __forceinline__ float bfhi(unsigned w) { return __uint_as_float(w & 0xffff0000u); }
; __device__ __forceinline__ float bf2f(bf16_t v) { return __uint_as_float(((unsigned)v) << 16); }
; __global__ void __launch_bounds__(512, 2) fwd_megakernel(Params PK) {
;     ...
; #pragma unroll 8
;                     for (int t = 0; t < 128; ++t) { const unsigned w = LRW[base + (size_t)t * DBR]; const float a = 1.0f - (float)(w & 0xffffu) * sc, g = bfhi(w); h = a * h + g;
;                         const float sg = bf2f(Hh[((size_t)bc * 128 + t) * LDH + C_GB + ch]);
;                         Ob[base + (size_t)t * DBR] = (bf16_t)(cvt_pk_bf16(h * sg, 0.f) & 0xffffu); } } }
	v_cvt_f32_u32_sdwa v21, v26 dst_sel:DWORD dst_unused:UNUSED_PAD src0_sel:WORD_0
	v_and_b32_e32 v17, 0xffff0000, v26
	v_fma_f32 v21, -v0, v21, 1.0
	v_fmac_f32_e32 v17, v14, v21
	v_lshlrev_b32_e32 v42, 16, v42
	v_mul_f32_e32 v42, v17, v42
	v_cvt_pk_bf16_f32 v42, v42, v1
	global_store_short v22, v42, s[68:69]
	s_waitcnt vmcnt(27)
	v_cvt_f32_u32_sdwa v21, v27 dst_sel:DWORD dst_unused:UNUSED_PAD src0_sel:WORD_0
	v_and_b32_e32 v14, 0xffff0000, v27
	v_fma_f32 v21, -v0, v21, 1.0
	v_fmac_f32_e32 v14, v17, v21
	v_lshlrev_b32_e32 v43, 16, v43
	v_mul_f32_e32 v43, v14, v43
	v_cvt_pk_bf16_f32 v43, v43, v1
	global_store_short v22, v43, s[68:69] offset:2048
	v_add_u32_e32 v22, 0x2ae06000, v6
	s_waitcnt vmcnt(26)
	v_cvt_f32_u32_sdwa v21, v28 dst_sel:DWORD dst_unused:UNUSED_PAD src0_sel:WORD_0
	v_and_b32_e32 v17, 0xffff0000, v28
	v_fma_f32 v21, -v0, v21, 1.0
	v_fmac_f32_e32 v17, v14, v21
	v_lshlrev_b32_e32 v44, 16, v44
	v_mul_f32_e32 v44, v17, v44
	v_cvt_pk_bf16_f32 v44, v44, v1
	global_store_short v22, v44, s[68:69] offset:-4096
	s_waitcnt vmcnt(25)
	v_cvt_f32_u32_sdwa v21, v29 dst_sel:DWORD dst_unused:UNUSED_PAD src0_sel:WORD_0
	v_and_b32_e32 v14, 0xffff0000, v29
	v_fma_f32 v21, -v0, v21, 1.0
	v_fmac_f32_e32 v14, v17, v21
	v_lshlrev_b32_e32 v45, 16, v45
	v_mul_f32_e32 v45, v14, v45
	v_cvt_pk_bf16_f32 v45, v45, v1
	global_store_short v22, v45, s[68:69] offset:-2048
	s_waitcnt vmcnt(24)
	v_cvt_f32_u32_sdwa v21, v30 dst_sel:DWORD dst_unused:UNUSED_PAD src0_sel:WORD_0
	v_and_b32_e32 v17, 0xffff0000, v30
	v_fma_f32 v21, -v0, v21, 1.0
	v_fmac_f32_e32 v17, v14, v21
	v_lshlrev_b32_e32 v46, 16, v46
	v_mul_f32_e32 v46, v17, v46
	v_cvt_pk_bf16_f32 v46, v46, v1
	global_store_short v22, v46, s[68:69]
	s_waitcnt vmcnt(23)
	v_cvt_f32_u32_sdwa v21, v31 dst_sel:DWORD dst_unused:UNUSED_PAD src0_sel:WORD_0
	v_and_b32_e32 v14, 0xffff0000, v31
	v_fma_f32 v21, -v0, v21, 1.0
	v_fmac_f32_e32 v14, v17, v21
	v_lshlrev_b32_e32 v47, 16, v47
	v_mul_f32_e32 v47, v14, v47
	v_cvt_pk_bf16_f32 v47, v47, v1
	global_store_short v22, v47, s[68:69] offset:2048
	v_add_u32_e32 v22, 0x2ae08000, v6
	s_waitcnt vmcnt(22)
	v_cvt_f32_u32_sdwa v21, v32 dst_sel:DWORD dst_unused:UNUSED_PAD src0_sel:WORD_0
	v_and_b32_e32 v17, 0xffff0000, v32
	v_fma_f32 v21, -v0, v21, 1.0
	v_fmac_f32_e32 v17, v14, v21
	v_lshlrev_b32_e32 v48, 16, v48
	v_mul_f32_e32 v48, v17, v48
	v_cvt_pk_bf16_f32 v48, v48, v1
	global_store_short v22, v48, s[68:69] offset:-4096
	s_waitcnt vmcnt(21)
	v_cvt_f32_u32_sdwa v21, v33 dst_sel:DWORD dst_unused:UNUSED_PAD src0_sel:WORD_0
	v_and_b32_e32 v14, 0xffff0000, v33
	v_fma_f32 v21, -v0, v21, 1.0
	v_fmac_f32_e32 v14, v17, v21
	v_lshlrev_b32_e32 v49, 16, v49
	v_mul_f32_e32 v49, v14, v49
	v_cvt_pk_bf16_f32 v49, v49, v1
	global_store_short v22, v49, s[68:69] offset:-2048
	s_waitcnt vmcnt(20)
	v_cvt_f32_u32_sdwa v21, v34 dst_sel:DWORD dst_unused:UNUSED_PAD src0_sel:WORD_0
	v_and_b32_e32 v17, 0xffff0000, v34
	v_fma_f32 v21, -v0, v21, 1.0
	v_fmac_f32_e32 v17, v14, v21
	v_lshlrev_b32_e32 v50, 16, v50
	v_mul_f32_e32 v50, v17, v50
	v_cvt_pk_bf16_f32 v50, v50, v1
	global_store_short v22, v50, s[68:69]
	s_waitcnt vmcnt(19)
	v_cvt_f32_u32_sdwa v21, v35 dst_sel:DWORD dst_unused:UNUSED_PAD src0_sel:WORD_0
	v_and_b32_e32 v14, 0xffff0000, v35
	v_fma_f32 v21, -v0, v21, 1.0
	v_fmac_f32_e32 v14, v17, v21
	v_lshlrev_b32_e32 v51, 16, v51
	v_mul_f32_e32 v51, v14, v51
	v_cvt_pk_bf16_f32 v51, v51, v1
	global_store_short v22, v51, s[68:69] offset:2048
	v_add_u32_e32 v22, 0x2ae0a000, v6
	s_waitcnt vmcnt(18)
	v_cvt_f32_u32_sdwa v21, v36 dst_sel:DWORD dst_unused:UNUSED_PAD src0_sel:WORD_0
	v_and_b32_e32 v17, 0xffff0000, v36
	v_fma_f32 v21, -v0, v21, 1.0
	v_fmac_f32_e32 v17, v14, v21
	v_lshlrev_b32_e32 v52, 16, v52
	v_mul_f32_e32 v52, v17, v52
	v_cvt_pk_bf16_f32 v52, v52, v1
	global_store_short v22, v52, s[68:69] offset:-4096
	s_waitcnt vmcnt(17)
	v_cvt_f32_u32_sdwa v21, v37 dst_sel:DWORD dst_unused:UNUSED_PAD src0_sel:WORD_0
	v_and_b32_e32 v14, 0xffff0000, v37
	v_fma_f32 v21, -v0, v21, 1.0
	v_fmac_f32_e32 v14, v17, v21
	v_lshlrev_b32_e32 v53, 16, v53
	v_mul_f32_e32 v53, v14, v53
	v_cvt_pk_bf16_f32 v53, v53, v1
	global_store_short v22, v53, s[68:69] offset:-2048
	s_waitcnt vmcnt(16)
	v_cvt_f32_u32_sdwa v21, v38 dst_sel:DWORD dst_unused:UNUSED_PAD src0_sel:WORD_0
	v_and_b32_e32 v17, 0xffff0000, v38
	v_fma_f32 v21, -v0, v21, 1.0
	v_fmac_f32_e32 v17, v14, v21
	v_lshlrev_b32_e32 v54, 16, v54
	v_mul_f32_e32 v54, v17, v54
	v_cvt_pk_bf16_f32 v54, v54, v1
	global_store_short v22, v54, s[68:69]
	s_waitcnt vmcnt(15)
	v_cvt_f32_u32_sdwa v21, v39 dst_sel:DWORD dst_unused:UNUSED_PAD src0_sel:WORD_0
	v_and_b32_e32 v14, 0xffff0000, v39
	v_fma_f32 v21, -v0, v21, 1.0
	v_fmac_f32_e32 v14, v17, v21
	v_lshlrev_b32_e32 v55, 16, v55
	v_mul_f32_e32 v55, v14, v55
	v_cvt_pk_bf16_f32 v55, v55, v1
	global_store_short v22, v55, s[68:69] offset:2048
	v_add_u32_e32 v6, 0x8000, v6
	s_cmp_eq_u32 s12, 0
	s_cbranch_scc0 .LBB0_762
	v_lshl_add_u64 v[2:3], v[2:3], 0, s[38:39]
	s_mov_b64 s[12:13], 0x1ffff
	v_cmp_lt_u64_e32 vcc, s[12:13], v[2:3]
	v_readlane_b32 s12, v253, 60
	s_or_b64 s[8:9], vcc, s[8:9]
	s_nop 0
	v_subrev_u16_e32 v16, s12, v16
	s_andn2_b64 exec, exec, s[8:9]
	s_cbranch_execnz .LBB0_757
	s_or_b64 exec, exec, s[8:9]
	s_add_u32 s4, s68, 0x33203000
	v_readlane_b32 s6, v255, 43
	s_addc_u32 s5, s69, 0
	v_readlane_b32 s7, v255, 44
	s_and_b64 s[6:7], s[6:7], exec
	v_readlane_b32 s8, v253, 62
	s_cselect_b32 s12, 0x10000, 0
	s_add_u32 s6, s68, 0x32e0301c
	v_readlane_b32 s9, v253, 63
	s_addc_u32 s7, s69, 0
	v_mov_b64_e32 v[8:9], v[166:167]
	v_lshl_add_u64 v[6:7], v[168:169], 2, s[8:9]
	s_mov_b64 s[8:9], 0

; __device__ __forceinline__ float bfhi(unsigned w) { return __uint_as_float(w & 0xffff0000u); }
; __global__ void __launch_bounds__(512, 2) fwd_megakernel(Params PK) {
;     ...
;                 for (size_t id = gtid; id < (size_t)128 * 1024; id += gstride) { const int ch = (int)(id & 1023), bc = (int)(id >> 10); const size_t base = (size_t)bc * 128 * DBR + ch;
;                     float p = 1.f, h = 0.f; const float sc = fmaxf(1.0f - __expf(-((const float*)(ws + WS_PEW1))[512 + ch]), 1e-30f) * (1.0f / 65535.0f);
; #pragma unroll 8
;                     for (int t = 0; t < 128; ++t) { const unsigned w = LRW[base + (size_t)t * DBR]; const float a = 1.0f - (float)(w & 0xffffu) * sc, g = bfhi(w); p *= a; h = a * h + g; }
;                     AGP[id] = p; AGH[id] = h; } }
.LBB0_776:
	v_lshl_add_u64 v[8:9], v[6:7], 0, s[14:15]
	v_add_co_u32_e32 v16, vcc, 0x20e04000, v8
	s_nop 1
	v_addc_co_u32_e32 v17, vcc, 0, v9, vcc
	global_load_dword v32, v[16:17], off offset:-4096
	global_load_dword v33, v[16:17], off
	v_add_co_u32_e32 v18, vcc, 0x20e06000, v8
	s_nop 1
	v_addc_co_u32_e32 v19, vcc, 0, v9, vcc
	global_load_dword v34, v[18:19], off offset:-4096
	global_load_dword v35, v[18:19], off
	v_add_co_u32_e32 v20, vcc, 0x20e08000, v8
	s_nop 1
	v_addc_co_u32_e32 v21, vcc, 0, v9, vcc
	global_load_dword v36, v[20:21], off offset:-4096
	global_load_dword v37, v[20:21], off
	v_add_co_u32_e32 v22, vcc, 0x20e0a000, v8
	s_nop 1
	v_addc_co_u32_e32 v23, vcc, 0, v9, vcc
	global_load_dword v38, v[22:23], off offset:-4096
	global_load_dword v39, v[22:23], off
	v_add_co_u32_e32 v24, vcc, 0x20e0c000, v8
	s_nop 1
	v_addc_co_u32_e32 v25, vcc, 0, v9, vcc
	global_load_dword v40, v[24:25], off offset:-4096
	global_load_dword v41, v[24:25], off
	v_add_co_u32_e32 v26, vcc, 0x20e0e000, v8
	s_nop 1
	v_addc_co_u32_e32 v27, vcc, 0, v9, vcc
	global_load_dword v42, v[26:27], off offset:-4096
	global_load_dword v43, v[26:27], off
	v_add_co_u32_e32 v28, vcc, 0x20e10000, v8
	s_nop 1
	v_addc_co_u32_e32 v29, vcc, 0, v9, vcc
	global_load_dword v44, v[28:29], off offset:-4096
	global_load_dword v45, v[28:29], off
	v_add_co_u32_e32 v30, vcc, 0x20e12000, v8
	s_nop 1
	v_addc_co_u32_e32 v31, vcc, 0, v9, vcc
	global_load_dword v46, v[30:31], off offset:-4096
	global_load_dword v47, v[30:31], off
	s_add_u32 s14, s14, 0x10000
	s_addc_u32 s15, s15, 0
	s_waitcnt vmcnt(15)
	v_cvt_f32_u32_sdwa v14, v32 dst_sel:DWORD dst_unused:UNUSED_PAD src0_sel:WORD_0
	v_and_b32_e32 v15, 0xffff0000, v32
	v_fma_f32 v14, -v0, v14, 1.0
	v_fmac_f32_e32 v15, v12, v14
	v_mul_f32_e32 v11, v11, v14
	s_waitcnt vmcnt(14)
	v_cvt_f32_u32_sdwa v14, v33 dst_sel:DWORD dst_unused:UNUSED_PAD src0_sel:WORD_0
	v_and_b32_e32 v12, 0xffff0000, v33
	v_fma_f32 v14, -v0, v14, 1.0
	v_fmac_f32_e32 v12, v15, v14
	v_mul_f32_e32 v11, v11, v14
	s_waitcnt vmcnt(13)
	v_cvt_f32_u32_sdwa v14, v34 dst_sel:DWORD dst_unused:UNUSED_PAD src0_sel:WORD_0
	v_and_b32_e32 v15, 0xffff0000, v34
	v_fma_f32 v14, -v0, v14, 1.0
	v_fmac_f32_e32 v15, v12, v14
	v_mul_f32_e32 v11, v11, v14
	s_waitcnt vmcnt(12)
	v_cvt_f32_u32_sdwa v14, v35 dst_sel:DWORD dst_unused:UNUSED_PAD src0_sel:WORD_0
	v_and_b32_e32 v12, 0xffff0000, v35
	v_fma_f32 v14, -v0, v14, 1.0
	v_fmac_f32_e32 v12, v15, v14
	v_mul_f32_e32 v11, v11, v14
	s_waitcnt vmcnt(11)
	v_cvt_f32_u32_sdwa v14, v36 dst_sel:DWORD dst_unused:UNUSED_PAD src0_sel:WORD_0
	v_and_b32_e32 v15, 0xffff0000, v36
	v_fma_f32 v14, -v0, v14, 1.0
	v_fmac_f32_e32 v15, v12, v14
	v_mul_f32_e32 v11, v11, v14
	s_waitcnt vmcnt(10)
	v_cvt_f32_u32_sdwa v14, v37 dst_sel:DWORD dst_unused:UNUSED_PAD src0_sel:WORD_0
	v_and_b32_e32 v12, 0xffff0000, v37
	v_fma_f32 v14, -v0, v14, 1.0
	v_fmac_f32_e32 v12, v15, v14
	v_mul_f32_e32 v11, v11, v14
	s_waitcnt vmcnt(9)
	v_cvt_f32_u32_sdwa v14, v38 dst_sel:DWORD dst_unused:UNUSED_PAD src0_sel:WORD_0
	v_and_b32_e32 v15, 0xffff0000, v38
	v_fma_f32 v14, -v0, v14, 1.0
	v_fmac_f32_e32 v15, v12, v14
	v_mul_f32_e32 v11, v11, v14
	s_waitcnt vmcnt(8)
	v_cvt_f32_u32_sdwa v14, v39 dst_sel:DWORD dst_unused:UNUSED_PAD src0_sel:WORD_0
	v_and_b32_e32 v12, 0xffff0000, v39
	v_fma_f32 v14, -v0, v14, 1.0
	v_fmac_f32_e32 v12, v15, v14
	v_mul_f32_e32 v11, v11, v14
	s_waitcnt vmcnt(7)
	v_cvt_f32_u32_sdwa v14, v40 dst_sel:DWORD dst_unused:UNUSED_PAD src0_sel:WORD_0
	v_and_b32_e32 v15, 0xffff0000, v40
	v_fma_f32 v14, -v0, v14, 1.0
	v_fmac_f32_e32 v15, v12, v14
	v_mul_f32_e32 v11, v11, v14
	s_waitcnt vmcnt(6)
	v_cvt_f32_u32_sdwa v14, v41 dst_sel:DWORD dst_unused:UNUSED_PAD src0_sel:WORD_0
	v_and_b32_e32 v12, 0xffff0000, v41
	v_fma_f32 v14, -v0, v14, 1.0
	v_fmac_f32_e32 v12, v15, v14
	v_mul_f32_e32 v11, v11, v14
	s_waitcnt vmcnt(5)
	v_cvt_f32_u32_sdwa v14, v42 dst_sel:DWORD dst_unused:UNUSED_PAD src0_sel:WORD_0
	v_and_b32_e32 v15, 0xffff0000, v42
	v_fma_f32 v14, -v0, v14, 1.0
	v_fmac_f32_e32 v15, v12, v14
	v_mul_f32_e32 v11, v11, v14
	s_waitcnt vmcnt(4)
	v_cvt_f32_u32_sdwa v14, v43 dst_sel:DWORD dst_unused:UNUSED_PAD src0_sel:WORD_0
	v_and_b32_e32 v12, 0xffff0000, v43
	v_fma_f32 v14, -v0, v14, 1.0
	v_fmac_f32_e32 v12, v15, v14
	v_mul_f32_e32 v11, v11, v14
	s_waitcnt vmcnt(3)
	v_cvt_f32_u32_sdwa v14, v44 dst_sel:DWORD dst_unused:UNUSED_PAD src0_sel:WORD_0
	v_and_b32_e32 v15, 0xffff0000, v44
	v_fma_f32 v14, -v0, v14, 1.0
	v_fmac_f32_e32 v15, v12, v14
	v_mul_f32_e32 v11, v11, v14
	s_waitcnt vmcnt(2)
	v_cvt_f32_u32_sdwa v14, v45 dst_sel:DWORD dst_unused:UNUSED_PAD src0_sel:WORD_0
	v_and_b32_e32 v12, 0xffff0000, v45
	v_fma_f32 v14, -v0, v14, 1.0
	v_fmac_f32_e32 v12, v15, v14
	v_mul_f32_e32 v11, v11, v14
	s_waitcnt vmcnt(1)
	v_cvt_f32_u32_sdwa v14, v46 dst_sel:DWORD dst_unused:UNUSED_PAD src0_sel:WORD_0
	v_and_b32_e32 v15, 0xffff0000, v46
	v_fma_f32 v14, -v0, v14, 1.0
	v_fmac_f32_e32 v15, v12, v14
	v_mul_f32_e32 v11, v11, v14
	s_waitcnt vmcnt(0)
	v_cvt_f32_u32_sdwa v14, v47 dst_sel:DWORD dst_unused:UNUSED_PAD src0_sel:WORD_0
	v_and_b32_e32 v12, 0xffff0000, v47
	v_fma_f32 v14, -v0, v14, 1.0
	v_fmac_f32_e32 v12, v15, v14
	v_mul_f32_e32 v11, v11, v14
	s_cmp_eq_u32 s14, 0x80000
	s_cbranch_scc0 .LBB0_776
	v_lshlrev_b64 v[6:7], 2, v[4:5]
	v_lshl_add_u64 v[4:5], v[4:5], 0, s[38:39]
	s_mov_b64 s[14:15], 0x1ffff
	v_cmp_lt_u64_e32 vcc, s[14:15], v[4:5]
	v_readlane_b32 s14, v253, 60
	v_lshl_add_u64 v[8:9], s[4:5], 0, v[6:7]
	v_lshl_add_u64 v[6:7], s[6:7], 0, v[6:7]
	v_lshl_add_u64 v[2:3], v[2:3], 0, s[60:61]
	s_or_b64 s[12:13], vcc, s[12:13]
	v_subrev_u16_e32 v10, s14, v10
	global_store_dword v[8:9], v11, off
	global_store_dword v[6:7], v12, off
	s_andn2_b64 exec, exec, s[12:13]
	s_cbranch_execnz .LBB0_775
